# FF: final RMS norm fused into the epilogue of the last GEMM phase (row sums of squares exchanged between the 4 workgroups of a row tile via returning atomics + a counter; halves of the workgroup re-al
# speedup vs baseline: 1.0167x; 1.0087x over previous
; __device__ __forceinline__ int otid() { int t = threadIdx.x; asm volatile("" : "+v"(t)); return t; }
; #define GAS __attribute__((address_space(1)))
; __device__ void phase_final(const Params& p) {
;     const int tid = otid(), lane = tid & 63, gw = blockIdx.x * 8 + (tid >> 6), nw = gridDim.x * 8;
;     GAS const f32x4* gf = (GAS const f32x4*)(unsigned long long)p.norm_final;
;     for (int row = gw; row < NL; row += nw) {
; __global__ void __launch_bounds__(512) mega(Params pk) {
;     ...
;             if (ph == 0) { const Params p = load_params(lp); phase_prep(p, lds); }
;             else if (ph == N_PHASES - 1) { const Params p = load_params(lp); phase_final(p); }
;             else if (sub == 0 || sub == 5) { const Params p = load_params(lp); phase_norm(p, l, sub == 5); }
;             else if (sub == 2) { const Params p = load_params(lp); phase_mix(p, l, lds); }
;             else { for (int gi = 0; gi < 6; ++gi) { if (!gemm_phase(lds, l, sub, gi, dry)) break; } }
.LBB0_16:
	s_cmp_lg_u32 s16, 17
	s_cbranch_scc1 .Lmy_ff_n17
	s_cmpk_lg_u32 s72, 0x100
	s_cbranch_scc1 .LBB0_644
	s_mov_b64 s[0:1], 0
	s_branch .LBB0_644
.Lmy_ff_n17:
	s_add_i32 s0, s16, 6
	s_cmp_lt_u32 s0, 15
	s_cselect_b64 s[0:1], -1, 0
	v_writelane_b32 v255, s0, 1
	s_mov_b64 s[6:7], -1
	s_cmp_lt_i32 s17, 3
	v_writelane_b32 v255, s1, 2
	s_mov_b64 s[0:1], 0
	v_writelane_b32 v255, s0, 3
	s_mov_b64 s[4:5], 0
	s_mov_b64 s[54:55], 0x8d80600
	v_writelane_b32 v255, s1, 4
	s_mov_b64 s[0:1], 0
	s_cbranch_scc1 .LBB0_27
	s_cmp_gt_i32 s17, 5
	s_cbranch_scc0 .LBB0_24
	s_cmp_gt_i32 s17, 7
	s_cbranch_scc0 .LBB0_21
	s_cmp_eq_u32 s17, 8
	s_mov_b64 s[6:7], 0
	s_cselect_b64 s[4:5], -1, 0

; #define GAS __attribute__((address_space(1)))
; __device__ __forceinline__ void gemm_epilogue(LAS unsigned char* lds, const GD& gd, const f32x4 (&acc)[2][2][4][2], const Unit& u) {
;     ...
; #pragma unroll
;         for (int am = 0; am < 8 / MBR; ++am) {
;             const int ai = (am * MBR) >> 2, m0 = (am * MBR) & 3;
;             f32x4 xi[MBR][2][2];
; #pragma unroll
;             for (int mm = 0; mm < MBR; ++mm)
; #pragma unroll
;                 for (int bj = 0; bj < 2; ++bj)
; #pragma unroll
;                     for (int n = 0; n < 2; ++n) xi[mm][bj][n] = *(GAS const f32x4*)(xin + xoff + (ai * HALF + (m0 + mm) * 16) * DM + bj * HALF + n * 16);
;             asm volatile("" ::: "memory");
; #pragma unroll
;             for (int mm = 0; mm < MBR; ++mm)
; #pragma unroll
;                 for (int bj = 0; bj < 2; ++bj)
; #pragma unroll
;                     for (int n = 0; n < 2; ++n) *(GAS f32x4*)(xout + xoff + (ai * HALF + (m0 + mm) * 16) * DM + bj * HALF + n * 16) = xi[mm][bj][n] + gv[bj][n] * acc[ai][bj][m0 + mm][n];
;         }
.LBB0_395:
	s_andn2_b64 vcc, exec, s[4:5]
	s_cbranch_vccnz .LBB0_397
	s_cmp_lg_u32 s17, 8
	s_cbranch_scc1 .Lmy_ff_orig
	v_readlane_b32 s2, v255, 0
	s_nop 3
	s_cmp_lg_u32 s2, 1
	s_cbranch_scc1 .Lmy_ff_orig
	s_cmpk_lg_u32 s72, 0x100
	s_cbranch_scc1 .Lmy_ff_orig
	v_lshlrev_b64 v[148:149], 2, v[96:97]
	v_lshl_add_u64 v[146:147], s[44:45], 0, v[148:149]
	v_lshl_add_u64 v[150:151], s[46:47], 0, v[148:149]
	s_mov_b64 s[4:5], 0x0
	v_lshl_add_u64 v[192:193], v[146:147], 0, s[4:5]
	s_mov_b64 s[4:5], 0x10000
	v_lshl_add_u64 v[194:195], v[146:147], 0, s[4:5]
	global_load_dwordx4 v[152:155], v[192:193], off
	global_load_dwordx4 v[156:159], v[192:193], off offset:64
	global_load_dwordx4 v[160:163], v[192:193], off offset:512
	global_load_dwordx4 v[164:167], v[192:193], off offset:576
	global_load_dwordx4 v[168:171], v[194:195], off
	global_load_dwordx4 v[172:175], v[194:195], off offset:64
	global_load_dwordx4 v[176:179], v[194:195], off offset:512
	global_load_dwordx4 v[180:183], v[194:195], off offset:576
	s_waitcnt vmcnt(0)
	v_pk_fma_f32 v[126:127], v[126:127], v[142:143], v[152:153]
	v_pk_fma_f32 v[128:129], v[128:129], v[144:145], v[154:155]
	v_pk_fma_f32 v[4:5], v[4:5], v[138:139], v[156:157]
	v_pk_fma_f32 v[6:7], v[6:7], v[140:141], v[158:159]
	v_pk_fma_f32 v[48:49], v[48:49], v[134:135], v[160:161]
	v_pk_fma_f32 v[50:51], v[50:51], v[136:137], v[162:163]
	v_pk_fma_f32 v[12:13], v[12:13], v[130:131], v[164:165]
	v_pk_fma_f32 v[14:15], v[14:15], v[132:133], v[166:167]
	v_pk_fma_f32 v[122:123], v[122:123], v[142:143], v[168:169]
	v_pk_fma_f32 v[124:125], v[124:125], v[144:145], v[170:171]
	v_pk_fma_f32 v[118:119], v[118:119], v[138:139], v[172:173]
	v_pk_fma_f32 v[120:121], v[120:121], v[140:141], v[174:175]
	v_pk_fma_f32 v[102:103], v[102:103], v[134:135], v[176:177]
	v_pk_fma_f32 v[104:105], v[104:105], v[136:137], v[178:179]
	v_pk_fma_f32 v[98:99], v[98:99], v[130:131], v[180:181]
	v_pk_fma_f32 v[100:101], v[100:101], v[132:133], v[182:183]
	s_mov_b64 s[4:5], 0x20000
	v_lshl_add_u64 v[192:193], v[146:147], 0, s[4:5]
	s_mov_b64 s[4:5], 0x30000
	v_lshl_add_u64 v[194:195], v[146:147], 0, s[4:5]
	global_load_dwordx4 v[152:155], v[192:193], off
	global_load_dwordx4 v[156:159], v[192:193], off offset:64
	global_load_dwordx4 v[160:163], v[192:193], off offset:512
	global_load_dwordx4 v[164:167], v[192:193], off offset:576
	global_load_dwordx4 v[168:171], v[194:195], off
	global_load_dwordx4 v[172:175], v[194:195], off offset:64
	global_load_dwordx4 v[176:179], v[194:195], off offset:512
	global_load_dwordx4 v[180:183], v[194:195], off offset:576
	s_waitcnt vmcnt(0)
	v_pk_fma_f32 v[114:115], v[114:115], v[142:143], v[152:153]
	v_pk_fma_f32 v[116:117], v[116:117], v[144:145], v[154:155]
	v_pk_fma_f32 v[110:111], v[110:111], v[138:139], v[156:157]
	v_pk_fma_f32 v[112:113], v[112:113], v[140:141], v[158:159]
	v_pk_fma_f32 v[92:93], v[92:93], v[134:135], v[160:161]
	v_pk_fma_f32 v[94:95], v[94:95], v[136:137], v[162:163]
	v_pk_fma_f32 v[88:89], v[88:89], v[130:131], v[164:165]
	v_pk_fma_f32 v[90:91], v[90:91], v[132:133], v[166:167]
	v_pk_fma_f32 v[106:107], v[106:107], v[142:143], v[168:169]
	v_pk_fma_f32 v[108:109], v[108:109], v[144:145], v[170:171]
	v_pk_fma_f32 v[8:9], v[8:9], v[138:139], v[172:173]
	v_pk_fma_f32 v[10:11], v[10:11], v[140:141], v[174:175]
	v_pk_fma_f32 v[44:45], v[44:45], v[134:135], v[176:177]
	v_pk_fma_f32 v[46:47], v[46:47], v[136:137], v[178:179]
	v_pk_fma_f32 v[16:17], v[16:17], v[130:131], v[180:181]
	v_pk_fma_f32 v[18:19], v[18:19], v[132:133], v[182:183]
	s_mov_b64 s[4:5], 0x80000
	v_lshl_add_u64 v[192:193], v[146:147], 0, s[4:5]
	s_mov_b64 s[4:5], 0x90000
	v_lshl_add_u64 v[194:195], v[146:147], 0, s[4:5]
	global_load_dwordx4 v[152:155], v[192:193], off
	global_load_dwordx4 v[156:159], v[192:193], off offset:64
	global_load_dwordx4 v[160:163], v[192:193], off offset:512
	global_load_dwordx4 v[164:167], v[192:193], off offset:576
	global_load_dwordx4 v[168:171], v[194:195], off
	global_load_dwordx4 v[172:175], v[194:195], off offset:64
	global_load_dwordx4 v[176:179], v[194:195], off offset:512
	global_load_dwordx4 v[180:183], v[194:195], off offset:576
	s_waitcnt vmcnt(0)
	v_pk_fma_f32 v[84:85], v[84:85], v[142:143], v[152:153]
	v_pk_fma_f32 v[86:87], v[86:87], v[144:145], v[154:155]
	v_pk_fma_f32 v[20:21], v[20:21], v[138:139], v[156:157]
	v_pk_fma_f32 v[22:23], v[22:23], v[140:141], v[158:159]
	v_pk_fma_f32 v[40:41], v[40:41], v[134:135], v[160:161]
	v_pk_fma_f32 v[42:43], v[42:43], v[136:137], v[162:163]
	v_pk_fma_f32 v[28:29], v[28:29], v[130:131], v[164:165]
	v_pk_fma_f32 v[30:31], v[30:31], v[132:133], v[166:167]
	v_pk_fma_f32 v[80:81], v[80:81], v[142:143], v[168:169]
	v_pk_fma_f32 v[82:83], v[82:83], v[144:145], v[170:171]
	v_pk_fma_f32 v[76:77], v[76:77], v[138:139], v[172:173]
	v_pk_fma_f32 v[78:79], v[78:79], v[140:141], v[174:175]
	v_pk_fma_f32 v[60:61], v[60:61], v[134:135], v[176:177]
	v_pk_fma_f32 v[62:63], v[62:63], v[136:137], v[178:179]
	v_pk_fma_f32 v[56:57], v[56:57], v[130:131], v[180:181]
	v_pk_fma_f32 v[58:59], v[58:59], v[132:133], v[182:183]
	s_mov_b64 s[4:5], 0xa0000
	v_lshl_add_u64 v[192:193], v[146:147], 0, s[4:5]
	s_mov_b64 s[4:5], 0xb0000
	v_lshl_add_u64 v[194:195], v[146:147], 0, s[4:5]
	global_load_dwordx4 v[152:155], v[192:193], off
	global_load_dwordx4 v[156:159], v[192:193], off offset:64
	global_load_dwordx4 v[160:163], v[192:193], off offset:512
	global_load_dwordx4 v[164:167], v[192:193], off offset:576
	global_load_dwordx4 v[168:171], v[194:195], off
	global_load_dwordx4 v[172:175], v[194:195], off offset:64
	global_load_dwordx4 v[176:179], v[194:195], off offset:512
	global_load_dwordx4 v[180:183], v[194:195], off offset:576
	s_waitcnt vmcnt(0)
; #define GAS __attribute__((address_space(1)))
; __device__ __forceinline__ void gemm_epilogue(LAS unsigned char* lds, const GD& gd, const f32x4 (&acc)[2][2][4][2], const Unit& u) {
;     ...
; #pragma unroll
;         for (int am = 0; am < 8 / MBR; ++am) {
;             const int ai = (am * MBR) >> 2, m0 = (am * MBR) & 3;
;             f32x4 xi[MBR][2][2];
; #pragma unroll
;             for (int mm = 0; mm < MBR; ++mm)
; #pragma unroll
;                 for (int bj = 0; bj < 2; ++bj)
; #pragma unroll
;                     for (int n = 0; n < 2; ++n) xi[mm][bj][n] = *(GAS const f32x4*)(xin + xoff + (ai * HALF + (m0 + mm) * 16) * DM + bj * HALF + n * 16);
;             asm volatile("" ::: "memory");
; #pragma unroll
;             for (int mm = 0; mm < MBR; ++mm)
; #pragma unroll
;                 for (int bj = 0; bj < 2; ++bj)
; #pragma unroll
;                     for (int n = 0; n < 2; ++n) *(GAS f32x4*)(xout + xoff + (ai * HALF + (m0 + mm) * 16) * DM + bj * HALF + n * 16) = xi[mm][bj][n] + gv[bj][n] * acc[ai][bj][m0 + mm][n];
;         }
; __device__ void phase_final(const Params& p) {
;     ...
;         float s = 0.f;
; #pragma unroll
;         for (int j = 0; j < 4; ++j) s += (v[j].x * v[j].x + v[j].y * v[j].y) + (v[j].z * v[j].z + v[j].w * v[j].w);
;         const float rstd = rsqrtf(wave_sum(s) * (1.f / 1024.f) + 1e-6f);
	v_pk_fma_f32 v[72:73], v[72:73], v[142:143], v[152:153]
	v_pk_fma_f32 v[74:75], v[74:75], v[144:145], v[154:155]
	v_pk_fma_f32 v[68:69], v[68:69], v[138:139], v[156:157]
	v_pk_fma_f32 v[70:71], v[70:71], v[140:141], v[158:159]
	v_pk_fma_f32 v[52:53], v[52:53], v[134:135], v[160:161]
	v_pk_fma_f32 v[54:55], v[54:55], v[136:137], v[162:163]
	v_pk_fma_f32 v[0:1], v[0:1], v[130:131], v[164:165]
	v_pk_fma_f32 v[2:3], v[2:3], v[132:133], v[166:167]
	v_pk_fma_f32 v[64:65], v[64:65], v[142:143], v[168:169]
	v_pk_fma_f32 v[66:67], v[66:67], v[144:145], v[170:171]
	v_pk_fma_f32 v[24:25], v[24:25], v[138:139], v[172:173]
	v_pk_fma_f32 v[26:27], v[26:27], v[140:141], v[174:175]
	v_pk_fma_f32 v[36:37], v[36:37], v[134:135], v[176:177]
	v_pk_fma_f32 v[38:39], v[38:39], v[136:137], v[178:179]
	v_pk_fma_f32 v[32:33], v[32:33], v[130:131], v[180:181]
	v_pk_fma_f32 v[34:35], v[34:35], v[132:133], v[182:183]
	v_pk_mul_f32 v[192:193], v[126:127], v[126:127]
	v_pk_fma_f32 v[192:193], v[128:129], v[128:129], v[192:193]
	v_pk_fma_f32 v[192:193], v[4:5], v[4:5], v[192:193]
	v_pk_fma_f32 v[192:193], v[6:7], v[6:7], v[192:193]
	v_pk_fma_f32 v[192:193], v[48:49], v[48:49], v[192:193]
	v_pk_fma_f32 v[192:193], v[50:51], v[50:51], v[192:193]
	v_pk_fma_f32 v[192:193], v[12:13], v[12:13], v[192:193]
	v_pk_fma_f32 v[192:193], v[14:15], v[14:15], v[192:193]
	v_add_f32_e32 v184, v192, v193
	v_pk_mul_f32 v[192:193], v[122:123], v[122:123]
	v_pk_fma_f32 v[192:193], v[124:125], v[124:125], v[192:193]
	v_pk_fma_f32 v[192:193], v[118:119], v[118:119], v[192:193]
	v_pk_fma_f32 v[192:193], v[120:121], v[120:121], v[192:193]
	v_pk_fma_f32 v[192:193], v[102:103], v[102:103], v[192:193]
	v_pk_fma_f32 v[192:193], v[104:105], v[104:105], v[192:193]
	v_pk_fma_f32 v[192:193], v[98:99], v[98:99], v[192:193]
	v_pk_fma_f32 v[192:193], v[100:101], v[100:101], v[192:193]
	v_add_f32_e32 v185, v192, v193
	v_pk_mul_f32 v[192:193], v[114:115], v[114:115]
	v_pk_fma_f32 v[192:193], v[116:117], v[116:117], v[192:193]
	v_pk_fma_f32 v[192:193], v[110:111], v[110:111], v[192:193]
	v_pk_fma_f32 v[192:193], v[112:113], v[112:113], v[192:193]
	v_pk_fma_f32 v[192:193], v[92:93], v[92:93], v[192:193]
	v_pk_fma_f32 v[192:193], v[94:95], v[94:95], v[192:193]
	v_pk_fma_f32 v[192:193], v[88:89], v[88:89], v[192:193]
	v_pk_fma_f32 v[192:193], v[90:91], v[90:91], v[192:193]
	v_add_f32_e32 v186, v192, v193
	v_pk_mul_f32 v[192:193], v[106:107], v[106:107]
	v_pk_fma_f32 v[192:193], v[108:109], v[108:109], v[192:193]
	v_pk_fma_f32 v[192:193], v[8:9], v[8:9], v[192:193]
	v_pk_fma_f32 v[192:193], v[10:11], v[10:11], v[192:193]
	v_pk_fma_f32 v[192:193], v[44:45], v[44:45], v[192:193]
	v_pk_fma_f32 v[192:193], v[46:47], v[46:47], v[192:193]
	v_pk_fma_f32 v[192:193], v[16:17], v[16:17], v[192:193]
	v_pk_fma_f32 v[192:193], v[18:19], v[18:19], v[192:193]
	v_add_f32_e32 v187, v192, v193
	v_pk_mul_f32 v[192:193], v[84:85], v[84:85]
	v_pk_fma_f32 v[192:193], v[86:87], v[86:87], v[192:193]
	v_pk_fma_f32 v[192:193], v[20:21], v[20:21], v[192:193]
	v_pk_fma_f32 v[192:193], v[22:23], v[22:23], v[192:193]
	v_pk_fma_f32 v[192:193], v[40:41], v[40:41], v[192:193]
	v_pk_fma_f32 v[192:193], v[42:43], v[42:43], v[192:193]
	v_pk_fma_f32 v[192:193], v[28:29], v[28:29], v[192:193]
	v_pk_fma_f32 v[192:193], v[30:31], v[30:31], v[192:193]
	v_add_f32_e32 v188, v192, v193
	v_pk_mul_f32 v[192:193], v[80:81], v[80:81]
	v_pk_fma_f32 v[192:193], v[82:83], v[82:83], v[192:193]
	v_pk_fma_f32 v[192:193], v[76:77], v[76:77], v[192:193]
	v_pk_fma_f32 v[192:193], v[78:79], v[78:79], v[192:193]
	v_pk_fma_f32 v[192:193], v[60:61], v[60:61], v[192:193]
	v_pk_fma_f32 v[192:193], v[62:63], v[62:63], v[192:193]
	v_pk_fma_f32 v[192:193], v[56:57], v[56:57], v[192:193]
	v_pk_fma_f32 v[192:193], v[58:59], v[58:59], v[192:193]
	v_add_f32_e32 v189, v192, v193
	v_pk_mul_f32 v[192:193], v[72:73], v[72:73]
	v_pk_fma_f32 v[192:193], v[74:75], v[74:75], v[192:193]
	v_pk_fma_f32 v[192:193], v[68:69], v[68:69], v[192:193]
	v_pk_fma_f32 v[192:193], v[70:71], v[70:71], v[192:193]
	v_pk_fma_f32 v[192:193], v[52:53], v[52:53], v[192:193]
	v_pk_fma_f32 v[192:193], v[54:55], v[54:55], v[192:193]
	v_pk_fma_f32 v[192:193], v[0:1], v[0:1], v[192:193]
	v_pk_fma_f32 v[192:193], v[2:3], v[2:3], v[192:193]
	v_add_f32_e32 v190, v192, v193
	v_pk_mul_f32 v[192:193], v[64:65], v[64:65]
	v_pk_fma_f32 v[192:193], v[66:67], v[66:67], v[192:193]
	v_pk_fma_f32 v[192:193], v[24:25], v[24:25], v[192:193]
	v_pk_fma_f32 v[192:193], v[26:27], v[26:27], v[192:193]
	v_pk_fma_f32 v[192:193], v[36:37], v[36:37], v[192:193]
	v_pk_fma_f32 v[192:193], v[38:39], v[38:39], v[192:193]
	v_pk_fma_f32 v[192:193], v[32:33], v[32:33], v[192:193]
	v_pk_fma_f32 v[192:193], v[34:35], v[34:35], v[192:193]
	v_add_f32_e32 v191, v192, v193
	s_cmp_lg_u32 s98, 0
	s_cbranch_scc1 .Lmy_ff_e0
	s_barrier
; __device__ __forceinline__ int otid() { int t = threadIdx.x; asm volatile("" : "+v"(t)); return t; }
; #define GAS __attribute__((address_space(1)))
; __device__ void phase_final(const Params& p) {
;     const int tid = otid(), lane = tid & 63, gw = blockIdx.x * 8 + (tid >> 6), nw = gridDim.x * 8;
;     GAS const f32x4* gf = (GAS const f32x4*)(unsigned long long)p.norm_final;
;     for (int row = gw; row < NL; row += nw) {
;         GAS f32x4* xr = (GAS f32x4*)(unsigned long long)(p.out + (size_t)row * DM);
;         f32x4 v[4], g4[4];
; #pragma unroll
;         for (int j = 0; j < 4; ++j) { v[j] = xr[lane + 64 * j]; g4[j] = gf[lane + 64 * j]; }
;         asm volatile("" ::: "memory");
;         float s = 0.f;
; #pragma unroll
;         for (int j = 0; j < 4; ++j) s += (v[j].x * v[j].x + v[j].y * v[j].y) + (v[j].z * v[j].z + v[j].w * v[j].w);
;         const float rstd = rsqrtf(wave_sum(s) * (1.f / 1024.f) + 1e-6f);
; #pragma unroll
;         for (int j = 0; j < 4; ++j) xr[lane + 64 * j] = v[j] * rstd * g4[j];
;     }
.Lmy_ff_e0:
	v_lshl_or_b32 v198, s98, 6, v252
	v_lshlrev_b32_e32 v194, 6, v198
	v_lshl_add_u32 v194, v251, 4, v194
	s_lshl_b32 s2, s15, 2
	s_add_i32 s2, s2, 0x20000
	v_add_u32_e32 v194, s2, v194
	ds_write_b32 v194, v184
	ds_write_b32 v194, v185 offset:1024
	ds_write_b32 v194, v186 offset:2048
	ds_write_b32 v194, v187 offset:3072
	ds_write_b32 v194, v188 offset:8192
	ds_write_b32 v194, v189 offset:9216
	ds_write_b32 v194, v190 offset:10240
	ds_write_b32 v194, v191 offset:11264
	s_waitcnt lgkmcnt(0)
	s_barrier
	s_cmp_lg_u32 s98, 0
	s_cbranch_scc1 .Lmy_ff_b1
	v_mov_b32_e32 v195, 0x240a8
	ds_read_b64 v[196:197], v195
	v_lshlrev_b32_e32 v194, 6, v210
	v_add_u32_e32 v194, 0x20000, v194
	ds_read_b128 v[152:155], v194
	ds_read_b128 v[156:159], v194 offset:16
	ds_read_b128 v[160:163], v194 offset:32
	ds_read_b128 v[164:167], v194 offset:48
	s_waitcnt lgkmcnt(0)
	v_readfirstlane_b32 s48, v196
	v_readfirstlane_b32 s49, v197
	v_add_f32_e32 v192, v152, v153
	v_add_f32_e32 v192, v192, v154
	v_add_f32_e32 v192, v192, v155
	v_add_f32_e32 v192, v192, v156
	v_add_f32_e32 v192, v192, v157
	v_add_f32_e32 v192, v192, v158
	v_add_f32_e32 v192, v192, v159
	v_add_f32_e32 v192, v192, v160
	v_add_f32_e32 v192, v192, v161
	v_add_f32_e32 v192, v192, v162
	v_add_f32_e32 v192, v192, v163
	v_add_f32_e32 v192, v192, v164
	v_add_f32_e32 v192, v192, v165
	v_add_f32_e32 v192, v192, v166
	v_add_f32_e32 v192, v192, v167
	s_add_u32 s50, s48, 0x100100
	s_addc_u32 s51, s49, 0
	s_lshl_b32 s2, s33, 2
	s_add_u32 s50, s50, s2
	s_addc_u32 s51, s51, 0
	s_add_u32 s48, s48, 0xf300000
	s_addc_u32 s49, s49, 0
	s_lshl_b32 s2, s33, 12
	s_add_u32 s48, s48, s2
	s_addc_u32 s49, s49, 0
	s_lshl_b32 s2, s80, 10
	v_lshlrev_b32_e32 v195, 2, v210
	v_add_u32_e32 v199, s2, v195
	global_atomic_swap v200, v199, v192, s[48:49] sc0
	s_waitcnt vmcnt(0)
.Lmy_ff_b1:
	s_barrier
	v_cmp_eq_u32_e32 vcc, 0, v210
	s_and_saveexec_b64 s[6:7], vcc
	s_cbranch_execz .Lmy_ff_nof
	v_mov_b32_e32 v198, 1
	global_atomic_add v97, v198, s[50:51]
	s_mov_b32 s2, 0
.Lmy_ff_spin:
	global_load_dword v199, v97, s[50:51] sc1
	s_waitcnt vmcnt(0)
	v_readfirstlane_b32 s4, v199
	s_nop 3
	s_cmp_ge_u32 s4, 4
	s_cbranch_scc1 .Lmy_ff_nof
	s_add_i32 s2, s2, 1
	s_cmp_lt_u32 s2, 0x4000
	s_cbranch_scc0 .Lmy_ff_nof
	s_sleep 1
	s_branch .Lmy_ff_spin
.Lmy_ff_nof:
	s_or_b64 exec, exec, s[6:7]
	s_barrier
	s_cmp_lg_u32 s98, 0
	s_cbranch_scc1 .Lmy_ff_b2
	v_mov_b32_e32 v200, 0
	global_atomic_add v152, v195, v200, s[48:49] sc0
	global_atomic_add v153, v195, v200, s[48:49] offset:1024 sc0
	global_atomic_add v154, v195, v200, s[48:49] offset:2048 sc0
	global_atomic_add v155, v195, v200, s[48:49] offset:3072 sc0
	v_mov_b32_e32 v196, 0x358637bd
	s_mov_b32 s2, 0x800000
	s_waitcnt vmcnt(0)
	v_add_f32_e32 v192, v152, v153
	v_add_f32_e32 v192, v192, v154
	v_add_f32_e32 v192, v192, v155
	v_fmamk_f32 v192, v192, 0x3a800000, v196
	v_cmp_gt_f32_e32 vcc, s2, v192
	v_mul_f32_e32 v193, 0x4b800000, v192
	s_nop 1
	v_cndmask_b32_e32 v192, v192, v193, vcc
	v_rsq_f32_e32 v192, v192
	s_nop 0
	v_mul_f32_e32 v193, 0x45800000, v192
	v_cndmask_b32_e32 v192, v192, v193, vcc
	v_add_u32_e32 v194, 0x20000, v195
	ds_write_b32 v194, v192
	s_waitcnt lgkmcnt(0)
.Lmy_ff_b2:
	s_barrier
	v_lshl_or_b32 v198, s98, 6, v252
	v_lshlrev_b32_e32 v194, 2, v198
	v_add_u32_e32 v194, 0x20000, v194
	ds_read_b32 v184, v194
	ds_read_b32 v185, v194 offset:64
	ds_read_b32 v186, v194 offset:128
	ds_read_b32 v187, v194 offset:192
	ds_read_b32 v188, v194 offset:512
	ds_read_b32 v189, v194 offset:576
	ds_read_b32 v190, v194 offset:640
	ds_read_b32 v191, v194 offset:704
	v_readlane_b32 s2, v254, 41
	s_nop 3
	v_mov_b32_e32 v195, s2
	ds_read_b64 v[196:197], v195
	v_lshlrev_b32_e32 v195, 2, v251
	v_lshl_or_b32 v195, s15, 5, v195
	v_lshlrev_b32_e32 v195, 2, v195
	s_waitcnt lgkmcnt(0)
	v_readfirstlane_b32 s4, v196
	v_readfirstlane_b32 s5, v197
	s_lshl_b32 s2, s80, 10
	s_add_u32 s4, s4, s2
	s_addc_u32 s5, s5, 0
	global_load_dwordx4 v[152:155], v195, s[4:5]
	global_load_dwordx4 v[156:159], v195, s[4:5] offset:64
	global_load_dwordx4 v[160:163], v195, s[4:5] offset:512
	global_load_dwordx4 v[164:167], v195, s[4:5] offset:576
	s_waitcnt vmcnt(0)
	s_mov_b64 s[4:5], 0x0
	v_lshl_add_u64 v[192:193], v[150:151], 0, s[4:5]
	v_mul_f32_e32 v126, v126, v184
	v_mul_f32_e32 v127, v127, v184
	v_mul_f32_e32 v128, v128, v184
	v_mul_f32_e32 v129, v129, v184
	v_pk_mul_f32 v[126:127], v[152:153], v[126:127]
	v_pk_mul_f32 v[128:129], v[154:155], v[128:129]
	global_store_dwordx4 v[192:193], v[126:129], off
	v_mul_f32_e32 v4, v4, v184
	v_mul_f32_e32 v5, v5, v184
	v_mul_f32_e32 v6, v6, v184
	v_mul_f32_e32 v7, v7, v184
	v_pk_mul_f32 v[4:5], v[156:157], v[4:5]
	v_pk_mul_f32 v[6:7], v[158:159], v[6:7]
	global_store_dwordx4 v[192:193], v[4:7], off offset:64
	v_mul_f32_e32 v48, v48, v184
	v_mul_f32_e32 v49, v49, v184
	v_mul_f32_e32 v50, v50, v184
	v_mul_f32_e32 v51, v51, v184
	v_pk_mul_f32 v[48:49], v[160:161], v[48:49]
	v_pk_mul_f32 v[50:51], v[162:163], v[50:51]
	global_store_dwordx4 v[192:193], v[48:51], off offset:512
	v_mul_f32_e32 v12, v12, v184
	v_mul_f32_e32 v13, v13, v184
	v_mul_f32_e32 v14, v14, v184
	v_mul_f32_e32 v15, v15, v184
	v_pk_mul_f32 v[12:13], v[164:165], v[12:13]
	v_pk_mul_f32 v[14:15], v[166:167], v[14:15]
	global_store_dwordx4 v[192:193], v[12:15], off offset:576
	s_mov_b64 s[4:5], 0x10000
	v_lshl_add_u64 v[192:193], v[150:151], 0, s[4:5]
	v_mul_f32_e32 v122, v122, v185
	v_mul_f32_e32 v123, v123, v185
	v_mul_f32_e32 v124, v124, v185
	v_mul_f32_e32 v125, v125, v185
	v_pk_mul_f32 v[122:123], v[152:153], v[122:123]
	v_pk_mul_f32 v[124:125], v[154:155], v[124:125]
	global_store_dwordx4 v[192:193], v[122:125], off
; __device__ void phase_final(const Params& p) {
;     ...
;         const float rstd = rsqrtf(wave_sum(s) * (1.f / 1024.f) + 1e-6f);
; #pragma unroll
;         for (int j = 0; j < 4; ++j) xr[lane + 64 * j] = v[j] * rstd * g4[j];
	v_mul_f32_e32 v118, v118, v185
	v_mul_f32_e32 v119, v119, v185
	v_mul_f32_e32 v120, v120, v185
	v_mul_f32_e32 v121, v121, v185
	v_pk_mul_f32 v[118:119], v[156:157], v[118:119]
	v_pk_mul_f32 v[120:121], v[158:159], v[120:121]
	global_store_dwordx4 v[192:193], v[118:121], off offset:64
	v_mul_f32_e32 v102, v102, v185
	v_mul_f32_e32 v103, v103, v185
	v_mul_f32_e32 v104, v104, v185
	v_mul_f32_e32 v105, v105, v185
	v_pk_mul_f32 v[102:103], v[160:161], v[102:103]
	v_pk_mul_f32 v[104:105], v[162:163], v[104:105]
	global_store_dwordx4 v[192:193], v[102:105], off offset:512
	v_mul_f32_e32 v98, v98, v185
	v_mul_f32_e32 v99, v99, v185
	v_mul_f32_e32 v100, v100, v185
	v_mul_f32_e32 v101, v101, v185
	v_pk_mul_f32 v[98:99], v[164:165], v[98:99]
	v_pk_mul_f32 v[100:101], v[166:167], v[100:101]
	global_store_dwordx4 v[192:193], v[98:101], off offset:576
	s_mov_b64 s[4:5], 0x20000
	v_lshl_add_u64 v[192:193], v[150:151], 0, s[4:5]
	v_mul_f32_e32 v114, v114, v186
	v_mul_f32_e32 v115, v115, v186
	v_mul_f32_e32 v116, v116, v186
	v_mul_f32_e32 v117, v117, v186
	v_pk_mul_f32 v[114:115], v[152:153], v[114:115]
	v_pk_mul_f32 v[116:117], v[154:155], v[116:117]
	global_store_dwordx4 v[192:193], v[114:117], off
	v_mul_f32_e32 v110, v110, v186
	v_mul_f32_e32 v111, v111, v186
	v_mul_f32_e32 v112, v112, v186
	v_mul_f32_e32 v113, v113, v186
	v_pk_mul_f32 v[110:111], v[156:157], v[110:111]
	v_pk_mul_f32 v[112:113], v[158:159], v[112:113]
	global_store_dwordx4 v[192:193], v[110:113], off offset:64
	v_mul_f32_e32 v92, v92, v186
	v_mul_f32_e32 v93, v93, v186
	v_mul_f32_e32 v94, v94, v186
	v_mul_f32_e32 v95, v95, v186
	v_pk_mul_f32 v[92:93], v[160:161], v[92:93]
	v_pk_mul_f32 v[94:95], v[162:163], v[94:95]
	global_store_dwordx4 v[192:193], v[92:95], off offset:512
	v_mul_f32_e32 v88, v88, v186
	v_mul_f32_e32 v89, v89, v186
	v_mul_f32_e32 v90, v90, v186
	v_mul_f32_e32 v91, v91, v186
	v_pk_mul_f32 v[88:89], v[164:165], v[88:89]
	v_pk_mul_f32 v[90:91], v[166:167], v[90:91]
	global_store_dwordx4 v[192:193], v[88:91], off offset:576
	s_mov_b64 s[4:5], 0x30000
	v_lshl_add_u64 v[192:193], v[150:151], 0, s[4:5]
	v_mul_f32_e32 v106, v106, v187
	v_mul_f32_e32 v107, v107, v187
	v_mul_f32_e32 v108, v108, v187
	v_mul_f32_e32 v109, v109, v187
	v_pk_mul_f32 v[106:107], v[152:153], v[106:107]
	v_pk_mul_f32 v[108:109], v[154:155], v[108:109]
	global_store_dwordx4 v[192:193], v[106:109], off
	v_mul_f32_e32 v8, v8, v187
	v_mul_f32_e32 v9, v9, v187
	v_mul_f32_e32 v10, v10, v187
	v_mul_f32_e32 v11, v11, v187
	v_pk_mul_f32 v[8:9], v[156:157], v[8:9]
	v_pk_mul_f32 v[10:11], v[158:159], v[10:11]
	global_store_dwordx4 v[192:193], v[8:11], off offset:64
	v_mul_f32_e32 v44, v44, v187
	v_mul_f32_e32 v45, v45, v187
	v_mul_f32_e32 v46, v46, v187
	v_mul_f32_e32 v47, v47, v187
	v_pk_mul_f32 v[44:45], v[160:161], v[44:45]
	v_pk_mul_f32 v[46:47], v[162:163], v[46:47]
	global_store_dwordx4 v[192:193], v[44:47], off offset:512
	v_mul_f32_e32 v16, v16, v187
	v_mul_f32_e32 v17, v17, v187
	v_mul_f32_e32 v18, v18, v187
	v_mul_f32_e32 v19, v19, v187
	v_pk_mul_f32 v[16:17], v[164:165], v[16:17]
	v_pk_mul_f32 v[18:19], v[166:167], v[18:19]
	global_store_dwordx4 v[192:193], v[16:19], off offset:576
	s_mov_b64 s[4:5], 0x80000
	v_lshl_add_u64 v[192:193], v[150:151], 0, s[4:5]
	v_mul_f32_e32 v84, v84, v188
	v_mul_f32_e32 v85, v85, v188
	v_mul_f32_e32 v86, v86, v188
	v_mul_f32_e32 v87, v87, v188
	v_pk_mul_f32 v[84:85], v[152:153], v[84:85]
	v_pk_mul_f32 v[86:87], v[154:155], v[86:87]
	global_store_dwordx4 v[192:193], v[84:87], off
	v_mul_f32_e32 v20, v20, v188
	v_mul_f32_e32 v21, v21, v188
	v_mul_f32_e32 v22, v22, v188
	v_mul_f32_e32 v23, v23, v188
	v_pk_mul_f32 v[20:21], v[156:157], v[20:21]
	v_pk_mul_f32 v[22:23], v[158:159], v[22:23]
	global_store_dwordx4 v[192:193], v[20:23], off offset:64
	v_mul_f32_e32 v40, v40, v188
	v_mul_f32_e32 v41, v41, v188
	v_mul_f32_e32 v42, v42, v188
	v_mul_f32_e32 v43, v43, v188
; #define PG8_WAIT_V(n) asm volatile("s_waitcnt vmcnt(" #n ")" ::: "memory")
; #define PG8_BAR __builtin_amdgcn_s_barrier()
; __device__ __forceinline__ bool gemm_phase(LAS unsigned char* lds, int l, int sub, int gi, bool dry = false) {
;     ...
;     PG8_WAIT_V(0);
;     if (wr == 0) PG8_BAR;
;     PG8_BAR;
; __device__ void phase_final(const Params& p) {
;     ...
;         const float rstd = rsqrtf(wave_sum(s) * (1.f / 1024.f) + 1e-6f);
; #pragma unroll
;         for (int j = 0; j < 4; ++j) xr[lane + 64 * j] = v[j] * rstd * g4[j];
	v_pk_mul_f32 v[40:41], v[160:161], v[40:41]
	v_pk_mul_f32 v[42:43], v[162:163], v[42:43]
	global_store_dwordx4 v[192:193], v[40:43], off offset:512
	v_mul_f32_e32 v28, v28, v188
	v_mul_f32_e32 v29, v29, v188
	v_mul_f32_e32 v30, v30, v188
	v_mul_f32_e32 v31, v31, v188
	v_pk_mul_f32 v[28:29], v[164:165], v[28:29]
	v_pk_mul_f32 v[30:31], v[166:167], v[30:31]
	global_store_dwordx4 v[192:193], v[28:31], off offset:576
	s_mov_b64 s[4:5], 0x90000
	v_lshl_add_u64 v[192:193], v[150:151], 0, s[4:5]
	v_mul_f32_e32 v80, v80, v189
	v_mul_f32_e32 v81, v81, v189
	v_mul_f32_e32 v82, v82, v189
	v_mul_f32_e32 v83, v83, v189
	v_pk_mul_f32 v[80:81], v[152:153], v[80:81]
	v_pk_mul_f32 v[82:83], v[154:155], v[82:83]
	global_store_dwordx4 v[192:193], v[80:83], off
	v_mul_f32_e32 v76, v76, v189
	v_mul_f32_e32 v77, v77, v189
	v_mul_f32_e32 v78, v78, v189
	v_mul_f32_e32 v79, v79, v189
	v_pk_mul_f32 v[76:77], v[156:157], v[76:77]
	v_pk_mul_f32 v[78:79], v[158:159], v[78:79]
	global_store_dwordx4 v[192:193], v[76:79], off offset:64
	v_mul_f32_e32 v60, v60, v189
	v_mul_f32_e32 v61, v61, v189
	v_mul_f32_e32 v62, v62, v189
	v_mul_f32_e32 v63, v63, v189
	v_pk_mul_f32 v[60:61], v[160:161], v[60:61]
	v_pk_mul_f32 v[62:63], v[162:163], v[62:63]
	global_store_dwordx4 v[192:193], v[60:63], off offset:512
	v_mul_f32_e32 v56, v56, v189
	v_mul_f32_e32 v57, v57, v189
	v_mul_f32_e32 v58, v58, v189
	v_mul_f32_e32 v59, v59, v189
	v_pk_mul_f32 v[56:57], v[164:165], v[56:57]
	v_pk_mul_f32 v[58:59], v[166:167], v[58:59]
	global_store_dwordx4 v[192:193], v[56:59], off offset:576
	s_mov_b64 s[4:5], 0xa0000
	v_lshl_add_u64 v[192:193], v[150:151], 0, s[4:5]
	v_mul_f32_e32 v72, v72, v190
	v_mul_f32_e32 v73, v73, v190
	v_mul_f32_e32 v74, v74, v190
	v_mul_f32_e32 v75, v75, v190
	v_pk_mul_f32 v[72:73], v[152:153], v[72:73]
	v_pk_mul_f32 v[74:75], v[154:155], v[74:75]
	global_store_dwordx4 v[192:193], v[72:75], off
	v_mul_f32_e32 v68, v68, v190
	v_mul_f32_e32 v69, v69, v190
	v_mul_f32_e32 v70, v70, v190
	v_mul_f32_e32 v71, v71, v190
	v_pk_mul_f32 v[68:69], v[156:157], v[68:69]
	v_pk_mul_f32 v[70:71], v[158:159], v[70:71]
	global_store_dwordx4 v[192:193], v[68:71], off offset:64
	v_mul_f32_e32 v52, v52, v190
	v_mul_f32_e32 v53, v53, v190
	v_mul_f32_e32 v54, v54, v190
	v_mul_f32_e32 v55, v55, v190
	v_pk_mul_f32 v[52:53], v[160:161], v[52:53]
	v_pk_mul_f32 v[54:55], v[162:163], v[54:55]
	global_store_dwordx4 v[192:193], v[52:55], off offset:512
	v_mul_f32_e32 v0, v0, v190
	v_mul_f32_e32 v1, v1, v190
	v_mul_f32_e32 v2, v2, v190
	v_mul_f32_e32 v3, v3, v190
	v_pk_mul_f32 v[0:1], v[164:165], v[0:1]
	v_pk_mul_f32 v[2:3], v[166:167], v[2:3]
	global_store_dwordx4 v[192:193], v[0:3], off offset:576
	s_mov_b64 s[4:5], 0xb0000
	v_lshl_add_u64 v[192:193], v[150:151], 0, s[4:5]
	v_mul_f32_e32 v64, v64, v191
	v_mul_f32_e32 v65, v65, v191
	v_mul_f32_e32 v66, v66, v191
	v_mul_f32_e32 v67, v67, v191
	v_pk_mul_f32 v[64:65], v[152:153], v[64:65]
	v_pk_mul_f32 v[66:67], v[154:155], v[66:67]
	global_store_dwordx4 v[192:193], v[64:67], off
	v_mul_f32_e32 v24, v24, v191
	v_mul_f32_e32 v25, v25, v191
	v_mul_f32_e32 v26, v26, v191
	v_mul_f32_e32 v27, v27, v191
	v_pk_mul_f32 v[24:25], v[156:157], v[24:25]
	v_pk_mul_f32 v[26:27], v[158:159], v[26:27]
	global_store_dwordx4 v[192:193], v[24:27], off offset:64
	v_mul_f32_e32 v36, v36, v191
	v_mul_f32_e32 v37, v37, v191
	v_mul_f32_e32 v38, v38, v191
	v_mul_f32_e32 v39, v39, v191
	v_pk_mul_f32 v[36:37], v[160:161], v[36:37]
	v_pk_mul_f32 v[38:39], v[162:163], v[38:39]
	global_store_dwordx4 v[192:193], v[36:39], off offset:512
	v_mul_f32_e32 v32, v32, v191
	v_mul_f32_e32 v33, v33, v191
	v_mul_f32_e32 v34, v34, v191
	v_mul_f32_e32 v35, v35, v191
	v_pk_mul_f32 v[32:33], v[164:165], v[32:33]
	v_pk_mul_f32 v[34:35], v[166:167], v[34:35]
	global_store_dwordx4 v[192:193], v[32:35], off offset:576
	s_nop 3
	s_cmp_lg_u32 s98, 1
	s_cbranch_scc1 .Lmy_ff_e1
	s_barrier

; #define GAS __attribute__((address_space(1)))
; __device__ __forceinline__ void gemm_epilogue(LAS unsigned char* lds, const GD& gd, const f32x4 (&acc)[2][2][4][2], const Unit& u) {
;     ...
; #pragma unroll
;         for (int am = 0; am < 8 / MBR; ++am) {
;             const int ai = (am * MBR) >> 2, m0 = (am * MBR) & 3;
;             f32x4 xi[MBR][2][2];
; #pragma unroll
;             for (int mm = 0; mm < MBR; ++mm)
; #pragma unroll
;                 for (int bj = 0; bj < 2; ++bj)
; #pragma unroll
;                     for (int n = 0; n < 2; ++n) xi[mm][bj][n] = *(GAS const f32x4*)(xin + xoff + (ai * HALF + (m0 + mm) * 16) * DM + bj * HALF + n * 16);
;             asm volatile("" ::: "memory");
; #pragma unroll
;             for (int mm = 0; mm < MBR; ++mm)
; #pragma unroll
;                 for (int bj = 0; bj < 2; ++bj)
; #pragma unroll
;                     for (int n = 0; n < 2; ++n) *(GAS f32x4*)(xout + xoff + (ai * HALF + (m0 + mm) * 16) * DM + bj * HALF + n * 16) = xi[mm][bj][n] + gv[bj][n] * acc[ai][bj][m0 + mm][n];
;         }
.Lmy_ff_orig:
	v_lshlrev_b64 v[148:149], 2, v[96:97]
	v_lshl_add_u64 v[146:147], s[44:45], 0, v[148:149]
	global_load_dwordx4 v[152:155], v[146:147], off
	global_load_dwordx4 v[156:159], v[146:147], off offset:64
	global_load_dwordx4 v[160:163], v[146:147], off offset:512
	global_load_dwordx4 v[164:167], v[146:147], off offset:576
	v_lshl_add_u64 v[150:151], s[46:47], 0, v[148:149]
	v_add_co_u32_e32 v148, vcc, 0x10000, v146
	s_mov_b32 s2, 0x10000
	s_nop 0
	v_addc_co_u32_e32 v149, vcc, 0, v147, vcc
	global_load_dwordx4 v[168:171], v[148:149], off
	global_load_dwordx4 v[172:175], v[148:149], off offset:64
	global_load_dwordx4 v[176:179], v[148:149], off offset:512
	global_load_dwordx4 v[180:183], v[148:149], off offset:576
	v_add_co_u32_e32 v148, vcc, s2, v150
	s_mov_b32 s2, 0x20000
	s_nop 0
	v_addc_co_u32_e32 v149, vcc, 0, v151, vcc
	s_mov_b32 s4, 0x30000
	s_waitcnt vmcnt(0)
	v_pk_fma_f32 v[154:155], v[128:129], v[144:145], v[154:155]
	v_pk_fma_f32 v[152:153], v[126:127], v[142:143], v[152:153]
	global_store_dwordx4 v[150:151], v[152:155], off
	s_nop 1
	v_pk_fma_f32 v[154:155], v[6:7], v[140:141], v[158:159]
	v_pk_fma_f32 v[152:153], v[4:5], v[138:139], v[156:157]
	global_store_dwordx4 v[150:151], v[152:155], off offset:64
	s_nop 1
	v_pk_fma_f32 v[154:155], v[50:51], v[136:137], v[162:163]
	v_pk_fma_f32 v[152:153], v[48:49], v[134:135], v[160:161]
	global_store_dwordx4 v[150:151], v[152:155], off offset:512
	s_nop 1
	v_pk_fma_f32 v[154:155], v[14:15], v[132:133], v[166:167]
	v_pk_fma_f32 v[152:153], v[12:13], v[130:131], v[164:165]
	global_store_dwordx4 v[150:151], v[152:155], off offset:576
	s_nop 1
	v_pk_fma_f32 v[154:155], v[124:125], v[144:145], v[170:171]
	v_pk_fma_f32 v[152:153], v[122:123], v[142:143], v[168:169]
	global_store_dwordx4 v[148:149], v[152:155], off
	s_nop 1
	v_pk_fma_f32 v[154:155], v[120:121], v[140:141], v[174:175]
	v_pk_fma_f32 v[152:153], v[118:119], v[138:139], v[172:173]
	global_store_dwordx4 v[148:149], v[152:155], off offset:64
	s_nop 1
	v_pk_fma_f32 v[154:155], v[104:105], v[136:137], v[178:179]
	v_pk_fma_f32 v[152:153], v[102:103], v[134:135], v[176:177]
	global_store_dwordx4 v[148:149], v[152:155], off offset:512
	s_nop 1
	v_pk_fma_f32 v[154:155], v[100:101], v[132:133], v[182:183]
	v_pk_fma_f32 v[152:153], v[98:99], v[130:131], v[180:181]
	global_store_dwordx4 v[148:149], v[152:155], off offset:576
	v_add_co_u32_e32 v148, vcc, s2, v146
	s_nop 1
	v_addc_co_u32_e32 v149, vcc, 0, v147, vcc
	global_load_dwordx4 v[152:155], v[148:149], off
	global_load_dwordx4 v[156:159], v[148:149], off offset:64
	global_load_dwordx4 v[160:163], v[148:149], off offset:512
	global_load_dwordx4 v[164:167], v[148:149], off offset:576
	v_add_co_u32_e32 v148, vcc, s4, v146
	s_waitcnt vmcnt(3)
	v_pk_fma_f32 v[154:155], v[116:117], v[144:145], v[154:155]
	v_addc_co_u32_e32 v149, vcc, 0, v147, vcc
	global_load_dwordx4 v[168:171], v[148:149], off
	global_load_dwordx4 v[172:175], v[148:149], off offset:64
	global_load_dwordx4 v[176:179], v[148:149], off offset:512
	global_load_dwordx4 v[180:183], v[148:149], off offset:576
	v_add_co_u32_e32 v148, vcc, s2, v150
	v_pk_fma_f32 v[152:153], v[114:115], v[142:143], v[152:153]
	s_nop 0
	v_addc_co_u32_e32 v149, vcc, 0, v151, vcc
	global_store_dwordx4 v[148:149], v[152:155], off
	s_mov_b32 s2, 0x80000
	s_waitcnt vmcnt(7)
	v_pk_fma_f32 v[154:155], v[112:113], v[140:141], v[158:159]
	v_pk_fma_f32 v[152:153], v[110:111], v[138:139], v[156:157]
	global_store_dwordx4 v[148:149], v[152:155], off offset:64
	s_waitcnt vmcnt(7)
	s_nop 0
	v_pk_fma_f32 v[154:155], v[94:95], v[136:137], v[162:163]
	v_pk_fma_f32 v[152:153], v[92:93], v[134:135], v[160:161]
	global_store_dwordx4 v[148:149], v[152:155], off offset:512
	s_waitcnt vmcnt(7)
	s_nop 0
	v_pk_fma_f32 v[154:155], v[90:91], v[132:133], v[166:167]
	v_pk_fma_f32 v[152:153], v[88:89], v[130:131], v[164:165]
	global_store_dwordx4 v[148:149], v[152:155], off offset:576
	v_add_co_u32_e32 v148, vcc, s4, v150
	s_mov_b32 s4, 0x90000
	s_nop 0
	v_addc_co_u32_e32 v149, vcc, 0, v151, vcc
	s_waitcnt vmcnt(7)
	v_pk_fma_f32 v[154:155], v[108:109], v[144:145], v[170:171]
	v_pk_fma_f32 v[152:153], v[106:107], v[142:143], v[168:169]
	global_store_dwordx4 v[148:149], v[152:155], off
	s_waitcnt vmcnt(7)
	s_nop 0
	v_pk_fma_f32 v[154:155], v[10:11], v[140:141], v[174:175]
	v_pk_fma_f32 v[152:153], v[8:9], v[138:139], v[172:173]
	global_store_dwordx4 v[148:149], v[152:155], off offset:64
	s_waitcnt vmcnt(7)
	s_nop 0
	v_pk_fma_f32 v[154:155], v[46:47], v[136:137], v[178:179]
	v_pk_fma_f32 v[152:153], v[44:45], v[134:135], v[176:177]
	global_store_dwordx4 v[148:149], v[152:155], off offset:512
	s_waitcnt vmcnt(7)
; #define GAS __attribute__((address_space(1)))
; __device__ __forceinline__ void gemm_epilogue(LAS unsigned char* lds, const GD& gd, const f32x4 (&acc)[2][2][4][2], const Unit& u) {
;     ...
; #pragma unroll
;         for (int am = 0; am < 8 / MBR; ++am) {
;             const int ai = (am * MBR) >> 2, m0 = (am * MBR) & 3;
;             f32x4 xi[MBR][2][2];
; #pragma unroll
;             for (int mm = 0; mm < MBR; ++mm)
; #pragma unroll
;                 for (int bj = 0; bj < 2; ++bj)
; #pragma unroll
;                     for (int n = 0; n < 2; ++n) xi[mm][bj][n] = *(GAS const f32x4*)(xin + xoff + (ai * HALF + (m0 + mm) * 16) * DM + bj * HALF + n * 16);
;             asm volatile("" ::: "memory");
; #pragma unroll
;             for (int mm = 0; mm < MBR; ++mm)
; #pragma unroll
;                 for (int bj = 0; bj < 2; ++bj)
; #pragma unroll
;                     for (int n = 0; n < 2; ++n) *(GAS f32x4*)(xout + xoff + (ai * HALF + (m0 + mm) * 16) * DM + bj * HALF + n * 16) = xi[mm][bj][n] + gv[bj][n] * acc[ai][bj][m0 + mm][n];
;         }
	s_nop 0
	v_pk_fma_f32 v[154:155], v[18:19], v[132:133], v[182:183]
	v_pk_fma_f32 v[152:153], v[16:17], v[130:131], v[180:181]
	global_store_dwordx4 v[148:149], v[152:155], off offset:576
	v_add_co_u32_e32 v148, vcc, s2, v146
	s_nop 1
	v_addc_co_u32_e32 v149, vcc, 0, v147, vcc
	global_load_dwordx4 v[152:155], v[148:149], off
	global_load_dwordx4 v[156:159], v[148:149], off offset:64
	global_load_dwordx4 v[160:163], v[148:149], off offset:512
	global_load_dwordx4 v[164:167], v[148:149], off offset:576
	v_add_co_u32_e32 v148, vcc, s4, v146
	s_waitcnt vmcnt(3)
	v_pk_fma_f32 v[154:155], v[86:87], v[144:145], v[154:155]
	v_addc_co_u32_e32 v149, vcc, 0, v147, vcc
	global_load_dwordx4 v[168:171], v[148:149], off
	global_load_dwordx4 v[172:175], v[148:149], off offset:64
	global_load_dwordx4 v[176:179], v[148:149], off offset:512
	global_load_dwordx4 v[180:183], v[148:149], off offset:576
	v_add_co_u32_e32 v148, vcc, s2, v150
	v_pk_fma_f32 v[152:153], v[84:85], v[142:143], v[152:153]
	s_nop 0
	v_addc_co_u32_e32 v149, vcc, 0, v151, vcc
	global_store_dwordx4 v[148:149], v[152:155], off
	s_mov_b32 s2, 0xb0000
	s_waitcnt vmcnt(7)
	v_pk_fma_f32 v[154:155], v[22:23], v[140:141], v[158:159]
	v_pk_fma_f32 v[152:153], v[20:21], v[138:139], v[156:157]
	global_store_dwordx4 v[148:149], v[152:155], off offset:64
	s_waitcnt vmcnt(7)
	s_nop 0
	v_pk_fma_f32 v[154:155], v[42:43], v[136:137], v[162:163]
	v_pk_fma_f32 v[152:153], v[40:41], v[134:135], v[160:161]
	global_store_dwordx4 v[148:149], v[152:155], off offset:512
	s_waitcnt vmcnt(7)
	s_nop 0
	v_pk_fma_f32 v[154:155], v[30:31], v[132:133], v[166:167]
	v_pk_fma_f32 v[152:153], v[28:29], v[130:131], v[164:165]
	global_store_dwordx4 v[148:149], v[152:155], off offset:576
	v_add_co_u32_e32 v148, vcc, s4, v150
	s_mov_b32 s4, 0xa0000
	s_nop 0
	v_addc_co_u32_e32 v149, vcc, 0, v151, vcc
	s_waitcnt vmcnt(7)
	v_pk_fma_f32 v[154:155], v[82:83], v[144:145], v[170:171]
	v_pk_fma_f32 v[152:153], v[80:81], v[142:143], v[168:169]
	global_store_dwordx4 v[148:149], v[152:155], off
	s_waitcnt vmcnt(7)
	s_nop 0
	v_pk_fma_f32 v[154:155], v[78:79], v[140:141], v[174:175]
	v_pk_fma_f32 v[152:153], v[76:77], v[138:139], v[172:173]
	global_store_dwordx4 v[148:149], v[152:155], off offset:64
	s_waitcnt vmcnt(7)
	s_nop 0
	v_pk_fma_f32 v[154:155], v[62:63], v[136:137], v[178:179]
	v_pk_fma_f32 v[152:153], v[60:61], v[134:135], v[176:177]
	global_store_dwordx4 v[148:149], v[152:155], off offset:512
	s_waitcnt vmcnt(7)
	s_nop 0
	v_pk_fma_f32 v[154:155], v[58:59], v[132:133], v[182:183]
	v_pk_fma_f32 v[152:153], v[56:57], v[130:131], v[180:181]
	global_store_dwordx4 v[148:149], v[152:155], off offset:576
	v_add_co_u32_e32 v148, vcc, s4, v146
	s_nop 1
	v_addc_co_u32_e32 v149, vcc, 0, v147, vcc
	v_add_co_u32_e32 v176, vcc, s2, v146
	global_load_dwordx4 v[152:155], v[148:149], off
	global_load_dwordx4 v[156:159], v[148:149], off offset:64
	global_load_dwordx4 v[160:163], v[148:149], off offset:512
	global_load_dwordx4 v[164:167], v[148:149], off offset:576
	v_addc_co_u32_e32 v177, vcc, 0, v147, vcc
	global_load_dwordx4 v[146:149], v[176:177], off
	global_load_dwordx4 v[168:171], v[176:177], off offset:64
	global_load_dwordx4 v[172:175], v[176:177], off offset:512
	s_nop 0
	global_load_dwordx4 v[176:179], v[176:177], off offset:576
	v_add_co_u32_e32 v180, vcc, s4, v150
	s_waitcnt vmcnt(7)
	v_pk_fma_f32 v[154:155], v[74:75], v[144:145], v[154:155]
	v_pk_fma_f32 v[152:153], v[72:73], v[142:143], v[152:153]
	v_addc_co_u32_e32 v181, vcc, 0, v151, vcc
	global_store_dwordx4 v[180:181], v[152:155], off
	s_waitcnt vmcnt(4)
	v_pk_fma_f32 v[142:143], v[64:65], v[142:143], v[146:147]
	v_add_co_u32_e32 v146, vcc, s2, v150
	v_pk_fma_f32 v[154:155], v[70:71], v[140:141], v[158:159]
	v_pk_fma_f32 v[152:153], v[68:69], v[138:139], v[156:157]
	global_store_dwordx4 v[180:181], v[152:155], off offset:64
	v_pk_fma_f32 v[144:145], v[66:67], v[144:145], v[148:149]
	v_addc_co_u32_e32 v147, vcc, 0, v151, vcc
	v_pk_fma_f32 v[154:155], v[54:55], v[136:137], v[162:163]
	v_pk_fma_f32 v[152:153], v[52:53], v[134:135], v[160:161]
	s_waitcnt vmcnt(4)
	v_pk_fma_f32 v[140:141], v[26:27], v[140:141], v[170:171]
	v_pk_fma_f32 v[138:139], v[24:25], v[138:139], v[168:169]
	s_waitcnt vmcnt(3)
	v_pk_fma_f32 v[136:137], v[38:39], v[136:137], v[174:175]
	v_pk_fma_f32 v[134:135], v[36:37], v[134:135], v[172:173]
	global_store_dwordx4 v[180:181], v[152:155], off offset:512
	global_store_dwordx4 v[146:147], v[142:145], off
	global_store_dwordx4 v[146:147], v[138:141], off offset:64
	v_pk_fma_f32 v[154:155], v[2:3], v[132:133], v[166:167]
	v_pk_fma_f32 v[152:153], v[0:1], v[130:131], v[164:165]
	global_store_dwordx4 v[146:147], v[134:137], off offset:512
	s_waitcnt vmcnt(6)
	v_pk_fma_f32 v[148:149], v[34:35], v[132:133], v[178:179]
	v_pk_fma_f32 v[146:147], v[32:33], v[130:131], v[176:177]
	global_store_dwordx4 v[180:181], v[152:155], off offset:576
